# hand-written P9 merge tail + P5..P8 code shifted by 8 bytes (placement)
# speedup vs baseline: 1.0144x; 1.0054x over previous
; __global__ void __launch_bounds__(NT, 2) mk_fwd(Args args) {
;     ...
;         for (int task_ = bx; task_ < 256 * RMUL(4); task_ += G) {
.Lp4_taskend:
	s_add_i32 s48, s48, s84
	s_cmpk_gt_i32 s48, 0xff
	s_cbranch_scc0 .Lp4_task
	s_nop 0
	s_nop 0

; __device__ __forceinline__ void xcd_barrier(const XcdBarrier& b) {
;     ...
;     }
;     __syncthreads();
.LBB0_811:
	s_or_b64 exec, exec, s[2:3]
	s_waitcnt lgkmcnt(0)
	s_barrier
	s_nop 0
	s_nop 0
	s_nop 0
	s_nop 0
	s_nop 0
	s_nop 0
	s_nop 0
	s_nop 0
	s_nop 0
	s_nop 0
	s_nop 0
	s_nop 0
	s_nop 0
	s_nop 0
